# prepass activation loads non-temporal (read once)
# speedup vs baseline: 1.0067x; 1.0067x over previous
; #define PP_LOAD(uu) do { const int c_ = (uu) & 31, bh_ = (uu) >> 5; const size_t rb_ = ((size_t)(bh_ >> 3) * SEQL + 64 * c_ + 16 * pi) * 1024 + (size_t)(bh_ & 7) * 128 + pk; \
;         _Pragma("unroll") for (int j = 0; j < 16; ++j) { const size_t a_ = rb_ + (size_t)j * 1024; lfr[j] = LOGF[a_]; qr[j] = Q[a_]; kr[j] = KK[a_]; } } while (0)
; __device__ __forceinline__ void hgrn_prepass(LAS unsigned char* lds, bf16* Q, bf16* KK, const float* LOGF, bf16* PBUF, float* DBUF, int bx, int G) {
;     ...
;     const int pk = tid & 127, pi = tid >> 7;
;     float lfr[16]; unsigned qr[16], kr[16];
;     ...
;     int u = bx;
;     if (u < 2048) PP_LOAD(u);
.LBB0_1152:
	s_or_b64 exec, exec, s[0:1]
	v_mov_b32_e32 v4, v145
	v_readlane_b32 s4, v253, 21
	s_waitcnt lgkmcnt(0)
	s_barrier
	v_readlane_b32 s5, v253, 22
	v_ashrrev_i32_e32 v14, 7, v4
	v_lshlrev_b32_e32 v6, 4, v14
	v_cndmask_b32_e64 v2, 0, 1, s[4:5]
	v_readfirstlane_b32 s2, v4
	v_and_b32_e32 v1, 0x7f, v4
	v_cmp_ne_u32_e64 s[0:1], 1, v2
	s_andn2_b64 vcc, exec, s[4:5]
	v_ashrrev_i32_e32 v7, 31, v6
	s_cbranch_vccnz .LBB0_1154
	v_readlane_b32 s4, v253, 23
	v_readlane_b32 s5, v253, 24
	v_readlane_b32 s3, v253, 25
	v_readlane_b32 s6, v253, 15
	v_lshl_add_u64 v[2:3], s[4:5], 0, v[6:7]
	v_lshlrev_b64 v[2:3], 10, v[2:3]
	v_or3_b32 v2, v1, s3, v2
	v_readlane_b32 s7, v253, 16
	v_readlane_b32 s4, v253, 0
	v_readlane_b32 s5, v253, 1
	v_lshl_add_u64 v[8:9], v[2:3], 2, s[6:7]
	global_load_dword v16, v[8:9], off nt
	v_lshlrev_b64 v[8:9], 1, v[2:3]
	v_lshl_add_u64 v[10:11], s[34:35], 0, v[8:9]
	v_lshl_add_u64 v[8:9], s[4:5], 0, v[8:9]
	global_load_ushort v15, v[10:11], off nt
	global_load_ushort v17, v[8:9], off nt
	v_or_b32_e32 v8, 0x400, v2
	v_mov_b32_e32 v9, v3
	v_lshl_add_u64 v[10:11], v[8:9], 2, s[6:7]
	v_lshlrev_b64 v[8:9], 1, v[8:9]
	global_load_dword v19, v[10:11], off nt
	v_lshl_add_u64 v[10:11], s[34:35], 0, v[8:9]
	v_lshl_add_u64 v[8:9], s[4:5], 0, v[8:9]
	global_load_ushort v18, v[10:11], off nt
	global_load_ushort v20, v[8:9], off nt
	v_or_b32_e32 v8, 0x800, v2
	v_mov_b32_e32 v9, v3
	v_lshl_add_u64 v[10:11], v[8:9], 2, s[6:7]
	v_lshlrev_b64 v[8:9], 1, v[8:9]
	global_load_dword v21, v[10:11], off nt
	v_lshl_add_u64 v[10:11], s[34:35], 0, v[8:9]
	v_lshl_add_u64 v[8:9], s[4:5], 0, v[8:9]
	global_load_ushort v22, v[10:11], off nt
	global_load_ushort v23, v[8:9], off nt
	v_or_b32_e32 v8, 0xc00, v2
	v_mov_b32_e32 v9, v3
	v_lshl_add_u64 v[10:11], v[8:9], 2, s[6:7]
	v_lshlrev_b64 v[8:9], 1, v[8:9]
	global_load_dword v25, v[10:11], off nt
	v_lshl_add_u64 v[10:11], s[34:35], 0, v[8:9]
	v_lshl_add_u64 v[8:9], s[4:5], 0, v[8:9]
	global_load_ushort v24, v[10:11], off nt
	global_load_ushort v26, v[8:9], off nt
	v_or_b32_e32 v8, 0x1000, v2
	v_mov_b32_e32 v9, v3
	v_lshl_add_u64 v[10:11], v[8:9], 2, s[6:7]
	v_lshlrev_b64 v[8:9], 1, v[8:9]
	global_load_dword v28, v[10:11], off nt
	v_lshl_add_u64 v[10:11], s[34:35], 0, v[8:9]
	v_lshl_add_u64 v[8:9], s[4:5], 0, v[8:9]
	global_load_ushort v27, v[10:11], off nt
	global_load_ushort v29, v[8:9], off nt
	v_or_b32_e32 v8, 0x1400, v2
	v_mov_b32_e32 v9, v3
	v_lshl_add_u64 v[10:11], v[8:9], 2, s[6:7]
	v_lshlrev_b64 v[8:9], 1, v[8:9]
	global_load_dword v31, v[10:11], off nt
	v_lshl_add_u64 v[10:11], s[34:35], 0, v[8:9]
	v_lshl_add_u64 v[8:9], s[4:5], 0, v[8:9]
	global_load_ushort v30, v[10:11], off nt
	global_load_ushort v32, v[8:9], off nt
	v_or_b32_e32 v8, 0x1800, v2
	v_mov_b32_e32 v9, v3
	v_lshl_add_u64 v[10:11], v[8:9], 2, s[6:7]
	v_lshlrev_b64 v[8:9], 1, v[8:9]
	global_load_dword v34, v[10:11], off nt
	v_lshl_add_u64 v[10:11], s[34:35], 0, v[8:9]
	v_lshl_add_u64 v[8:9], s[4:5], 0, v[8:9]
	global_load_ushort v33, v[10:11], off nt
	global_load_ushort v35, v[8:9], off nt
	v_or_b32_e32 v8, 0x1c00, v2
	v_mov_b32_e32 v9, v3
	v_lshl_add_u64 v[10:11], v[8:9], 2, s[6:7]
	v_lshlrev_b64 v[8:9], 1, v[8:9]
	global_load_dword v37, v[10:11], off nt
	v_lshl_add_u64 v[10:11], s[34:35], 0, v[8:9]
	v_lshl_add_u64 v[8:9], s[4:5], 0, v[8:9]
	global_load_ushort v36, v[10:11], off nt
	global_load_ushort v38, v[8:9], off nt
	v_or_b32_e32 v8, 0x2000, v2
	v_mov_b32_e32 v9, v3
	v_lshl_add_u64 v[10:11], v[8:9], 2, s[6:7]
	v_lshlrev_b64 v[8:9], 1, v[8:9]
	global_load_dword v40, v[10:11], off nt
	v_lshl_add_u64 v[10:11], s[34:35], 0, v[8:9]
	v_lshl_add_u64 v[8:9], s[4:5], 0, v[8:9]
	global_load_ushort v39, v[10:11], off nt
	global_load_ushort v41, v[8:9], off nt
	v_or_b32_e32 v8, 0x2400, v2
	v_mov_b32_e32 v9, v3
	v_lshl_add_u64 v[10:11], v[8:9], 2, s[6:7]
	v_lshlrev_b64 v[8:9], 1, v[8:9]
	global_load_dword v43, v[10:11], off nt
	v_lshl_add_u64 v[10:11], s[34:35], 0, v[8:9]
	v_lshl_add_u64 v[8:9], s[4:5], 0, v[8:9]
	global_load_ushort v42, v[10:11], off nt
	global_load_ushort v44, v[8:9], off nt
	v_or_b32_e32 v8, 0x2800, v2
	v_mov_b32_e32 v9, v3
	v_lshl_add_u64 v[10:11], v[8:9], 2, s[6:7]
	v_lshlrev_b64 v[8:9], 1, v[8:9]
	global_load_dword v45, v[10:11], off nt
	v_lshl_add_u64 v[10:11], s[34:35], 0, v[8:9]
	v_lshl_add_u64 v[8:9], s[4:5], 0, v[8:9]
	global_load_ushort v46, v[10:11], off nt
	global_load_ushort v49, v[8:9], off nt
	v_or_b32_e32 v8, 0x2c00, v2
	v_mov_b32_e32 v9, v3
	v_lshl_add_u64 v[10:11], v[8:9], 2, s[6:7]
	v_lshlrev_b64 v[8:9], 1, v[8:9]
	global_load_dword v69, v[10:11], off nt
	v_lshl_add_u64 v[10:11], s[34:35], 0, v[8:9]
	v_lshl_add_u64 v[8:9], s[4:5], 0, v[8:9]
	global_load_ushort v52, v[10:11], off nt
	global_load_ushort v68, v[8:9], off nt
	v_or_b32_e32 v8, 0x3000, v2
	v_mov_b32_e32 v9, v3
	v_lshl_add_u64 v[10:11], v[8:9], 2, s[6:7]
	v_lshlrev_b64 v[8:9], 1, v[8:9]
	global_load_dword v72, v[10:11], off nt
	v_lshl_add_u64 v[10:11], s[34:35], 0, v[8:9]
	v_lshl_add_u64 v[8:9], s[4:5], 0, v[8:9]
	global_load_ushort v70, v[10:11], off nt
	global_load_ushort v71, v[8:9], off nt
	v_or_b32_e32 v8, 0x3400, v2
	v_mov_b32_e32 v9, v3
	v_lshl_add_u64 v[10:11], v[8:9], 2, s[6:7]
	v_lshlrev_b64 v[8:9], 1, v[8:9]
	global_load_dword v93, v[10:11], off nt
	v_lshl_add_u64 v[10:11], s[34:35], 0, v[8:9]
	v_lshl_add_u64 v[8:9], s[4:5], 0, v[8:9]
	global_load_ushort v73, v[10:11], off nt
	global_load_ushort v91, v[8:9], off nt
	v_or_b32_e32 v8, 0x3800, v2
	v_mov_b32_e32 v9, v3
	v_lshl_add_u64 v[10:11], v[8:9], 2, s[6:7]
	v_lshlrev_b64 v[8:9], 1, v[8:9]
	global_load_dword v95, v[10:11], off nt
	v_lshl_add_u64 v[10:11], s[34:35], 0, v[8:9]
	v_lshl_add_u64 v[8:9], s[4:5], 0, v[8:9]
	v_or_b32_e32 v2, 0x3c00, v2
	global_load_ushort v92, v[10:11], off nt
	global_load_ushort v94, v[8:9], off nt
	v_lshl_add_u64 v[8:9], v[2:3], 2, s[6:7]
	v_lshlrev_b64 v[2:3], 1, v[2:3]
	global_load_dword v97, v[8:9], off nt
	v_lshl_add_u64 v[8:9], s[34:35], 0, v[2:3]
	v_lshl_add_u64 v[2:3], s[4:5], 0, v[2:3]
	global_load_ushort v96, v[8:9], off nt
	global_load_ushort v98, v[2:3], off nt

; __device__ __forceinline__ float bf2f(unsigned short u) { return __uint_as_float((unsigned)u << 16); }
; __device__ __forceinline__ unsigned short f2bf(float f) { return (unsigned short)(pk2(f, 0.f) & 0xffffu); }
; __device__ __forceinline__ void hgrn_prepass(LAS unsigned char* lds, bf16* Q, bf16* KK, const float* LOGF, bf16* PBUF, float* DBUF, int bx, int G) {
;     ...
;     for (; u < 2048; u += G) {
;         const int c = u & 31, bh = u >> 5; const size_t m0 = (size_t)(bh >> 3) * SEQL + 64 * c; const int hc = (bh & 7) * 128;
;         {
;             float bl[16], kkv[16]; float bsum = 0.f;
; #pragma unroll
;             for (int j = 0; j < 16; ++j) {
;                 const float q = bf2f((unsigned short)qr[j]); const float kk = bf2f((unsigned short)kr[j]);
;                 bsum += lfr[j]; bl[j] = bsum; kkv[j] = kk;
;                 Qt[(16 * pi + j) * 136 + pk] = f2bf(q * __expf(bsum));
;                 Kt[(16 * pi + j) * 136 + pk] = f2bf(kk * __expf(fminf(-bsum, 80.f)));
;             }
.LBB0_1157:
	s_waitcnt vmcnt(62)
	v_add_f32_e32 v3, 0, v16
	v_mul_f32_e32 v5, 0x3fb8aa3b, v3
	v_exp_f32_e32 v5, v5
	v_lshlrev_b32_e32 v4, 16, v15
	s_mov_b32 s2, 0x42a00000
	v_lshlrev_b32_e32 v2, 16, v17
	v_mul_f32_e32 v4, v5, v4
	v_cvt_pk_bf16_f32 v4, v4, s0
	ds_write_b16 v51, v4
	v_min_f32_e64 v4, -v3, s2
	v_add_f32_e32 v5, v3, v19
	v_mul_f32_e32 v4, 0x3fb8aa3b, v4
	v_mul_f32_e32 v12, 0x3fb8aa3b, v5
	v_exp_f32_e32 v4, v4
	v_exp_f32_e32 v12, v12
	v_lshlrev_b32_e32 v11, 16, v18
	v_lshlrev_b32_e32 v13, 16, v22
	v_mul_f32_e32 v4, v4, v2
	v_mul_f32_e32 v11, v12, v11
	v_cvt_pk_bf16_f32 v4, v4, s0
	v_cvt_pk_bf16_f32 v11, v11, s0
	ds_write_b16 v51, v4 offset:17408
	ds_write_b16 v53, v11
	v_min_f32_e64 v11, -v5, s2
	v_add_f32_e32 v12, v5, v21
	v_mul_f32_e32 v11, 0x3fb8aa3b, v11
	v_mul_f32_e32 v99, 0x3fb8aa3b, v12
	v_exp_f32_e32 v11, v11
	v_exp_f32_e32 v99, v99
	v_lshlrev_b32_e32 v4, 16, v20
	v_lshlrev_b32_e32 v100, 16, v24
	v_mul_f32_e32 v11, v11, v4
	v_mul_f32_e32 v13, v99, v13
	v_cvt_pk_bf16_f32 v11, v11, s0
	v_cvt_pk_bf16_f32 v13, v13, s0
	ds_write_b16 v53, v11 offset:17408
	ds_write_b16 v54, v13
	v_min_f32_e64 v13, -v12, s2
	v_add_f32_e32 v99, v12, v25
	v_mul_f32_e32 v13, 0x3fb8aa3b, v13
	v_mul_f32_e32 v101, 0x3fb8aa3b, v99
	v_exp_f32_e32 v13, v13
	v_exp_f32_e32 v101, v101
	v_lshlrev_b32_e32 v11, 16, v23
	v_lshlrev_b32_e32 v102, 16, v27
	v_mul_f32_e32 v13, v13, v11
	v_mul_f32_e32 v100, v101, v100
	v_cvt_pk_bf16_f32 v13, v13, s0
	v_cvt_pk_bf16_f32 v100, v100, s0
	ds_write_b16 v54, v13 offset:17408
	ds_write_b16 v55, v100
	v_min_f32_e64 v100, -v99, s2
	v_add_f32_e32 v101, v99, v28
	v_mul_f32_e32 v100, 0x3fb8aa3b, v100
	v_mul_f32_e32 v103, 0x3fb8aa3b, v101
	v_exp_f32_e32 v100, v100
	v_exp_f32_e32 v103, v103
	v_lshlrev_b32_e32 v13, 16, v26
	v_lshlrev_b32_e32 v104, 16, v30
	v_mul_f32_e32 v100, v100, v13
	v_mul_f32_e32 v102, v103, v102
	v_cvt_pk_bf16_f32 v100, v100, s0
	v_cvt_pk_bf16_f32 v102, v102, s0
	ds_write_b16 v55, v100 offset:17408
	ds_write_b16 v56, v102
	v_min_f32_e64 v102, -v101, s2
	v_add_f32_e32 v103, v101, v31
	v_mul_f32_e32 v102, 0x3fb8aa3b, v102
	v_mul_f32_e32 v105, 0x3fb8aa3b, v103
	v_exp_f32_e32 v102, v102
	v_exp_f32_e32 v105, v105
	v_lshlrev_b32_e32 v100, 16, v29
	s_waitcnt vmcnt(61)
	v_add_f32_e32 v106, v103, v34
	v_mul_f32_e32 v102, v102, v100
	v_mul_f32_e32 v104, v105, v104
	v_cvt_pk_bf16_f32 v102, v102, s0
	v_cvt_pk_bf16_f32 v104, v104, s0
	ds_write_b16 v56, v102 offset:17408
	ds_write_b16 v57, v104
	v_min_f32_e64 v104, -v103, s2
	v_mul_f32_e32 v104, 0x3fb8aa3b, v104
	v_exp_f32_e32 v104, v104
	v_mul_f32_e32 v107, 0x3fb8aa3b, v106
	v_lshlrev_b32_e32 v102, 16, v32
	v_exp_f32_e32 v107, v107
	v_mul_f32_e32 v104, v104, v102
	v_cvt_pk_bf16_f32 v104, v104, s0
	ds_write_b16 v57, v104 offset:17408
	s_waitcnt vmcnt(60)
	v_lshlrev_b32_e32 v104, 16, v33
	v_mul_f32_e32 v104, v107, v104
	v_cvt_pk_bf16_f32 v104, v104, s0
	ds_write_b16 v58, v104
	v_min_f32_e64 v104, -v106, s2
	v_mul_f32_e32 v104, 0x3fb8aa3b, v104
	v_exp_f32_e32 v104, v104
	s_waitcnt vmcnt(58)
	v_add_f32_e32 v108, v106, v37
	v_mul_f32_e32 v109, 0x3fb8aa3b, v108
	v_lshlrev_b32_e32 v105, 16, v35
	v_exp_f32_e32 v109, v109
	v_mul_f32_e32 v104, v104, v105
	v_cvt_pk_bf16_f32 v104, v104, s0
	ds_write_b16 v58, v104 offset:17408
	s_waitcnt vmcnt(57)
	v_lshlrev_b32_e32 v104, 16, v36
	v_mul_f32_e32 v104, v109, v104
	v_cvt_pk_bf16_f32 v104, v104, s0
	ds_write_b16 v59, v104
	v_min_f32_e64 v104, -v108, s2
	v_mul_f32_e32 v104, 0x3fb8aa3b, v104
	v_exp_f32_e32 v104, v104
	s_waitcnt vmcnt(55)
	v_add_f32_e32 v110, v108, v40
	v_mul_f32_e32 v111, 0x3fb8aa3b, v110
	v_lshlrev_b32_e32 v107, 16, v38
	v_exp_f32_e32 v111, v111
	v_mul_f32_e32 v104, v104, v107
	v_cvt_pk_bf16_f32 v104, v104, s0
	ds_write_b16 v59, v104 offset:17408
	s_waitcnt vmcnt(54)
	v_lshlrev_b32_e32 v104, 16, v39
	v_mul_f32_e32 v104, v111, v104
	v_cvt_pk_bf16_f32 v104, v104, s0
	ds_write_b16 v60, v104
	v_min_f32_e64 v104, -v110, s2
	v_mul_f32_e32 v104, 0x3fb8aa3b, v104
	v_exp_f32_e32 v104, v104
	s_waitcnt vmcnt(52)
	v_add_f32_e32 v112, v110, v43
	v_mul_f32_e32 v113, 0x3fb8aa3b, v112
	v_lshlrev_b32_e32 v109, 16, v41
	v_exp_f32_e32 v113, v113
	v_mul_f32_e32 v104, v104, v109
	v_cvt_pk_bf16_f32 v104, v104, s0
	ds_write_b16 v60, v104 offset:17408
	s_waitcnt vmcnt(51)
	v_lshlrev_b32_e32 v104, 16, v42
	v_mul_f32_e32 v104, v113, v104
	v_cvt_pk_bf16_f32 v104, v104, s0
	ds_write_b16 v61, v104
	v_min_f32_e64 v104, -v112, s2
	v_mul_f32_e32 v104, 0x3fb8aa3b, v104
	v_exp_f32_e32 v104, v104
	s_waitcnt vmcnt(49)
	v_add_f32_e32 v114, v112, v45
	v_mul_f32_e32 v115, 0x3fb8aa3b, v114
	v_lshlrev_b32_e32 v111, 16, v44
	v_exp_f32_e32 v115, v115
	v_mul_f32_e32 v104, v104, v111
	v_cvt_pk_bf16_f32 v104, v104, s0
	ds_write_b16 v61, v104 offset:17408
	s_waitcnt vmcnt(48)
	v_lshlrev_b32_e32 v104, 16, v46
	v_mul_f32_e32 v104, v115, v104
	v_cvt_pk_bf16_f32 v104, v104, s0
	ds_write_b16 v62, v104
	v_min_f32_e64 v104, -v114, s2
	v_mul_f32_e32 v104, 0x3fb8aa3b, v104
	v_exp_f32_e32 v104, v104
	s_waitcnt vmcnt(46)
	v_add_f32_e32 v116, v114, v69
	v_mul_f32_e32 v117, 0x3fb8aa3b, v116
	v_lshlrev_b32_e32 v113, 16, v49
	v_exp_f32_e32 v117, v117
	v_mul_f32_e32 v104, v104, v113
	v_cvt_pk_bf16_f32 v104, v104, s0
	ds_write_b16 v62, v104 offset:17408
	s_waitcnt vmcnt(45)
	v_lshlrev_b32_e32 v104, 16, v52
	v_mul_f32_e32 v104, v117, v104
	v_cvt_pk_bf16_f32 v104, v104, s0
	ds_write_b16 v63, v104
	v_min_f32_e64 v104, -v116, s2
	v_mul_f32_e32 v104, 0x3fb8aa3b, v104
	v_exp_f32_e32 v104, v104
	s_waitcnt vmcnt(43)
	v_add_f32_e32 v118, v116, v72
	v_mul_f32_e32 v119, 0x3fb8aa3b, v118
	v_lshlrev_b32_e32 v115, 16, v68
	v_exp_f32_e32 v119, v119
	v_mul_f32_e32 v104, v104, v115
	v_cvt_pk_bf16_f32 v104, v104, s0
	ds_write_b16 v63, v104 offset:17408
	s_waitcnt vmcnt(42)
; __device__ __forceinline__ float bf2f(unsigned short u) { return __uint_as_float((unsigned)u << 16); }
; __device__ __forceinline__ unsigned short f2bf(float f) { return (unsigned short)(pk2(f, 0.f) & 0xffffu); }
; #define PP_LOAD(uu) do { const int c_ = (uu) & 31, bh_ = (uu) >> 5; const size_t rb_ = ((size_t)(bh_ >> 3) * SEQL + 64 * c_ + 16 * pi) * 1024 + (size_t)(bh_ & 7) * 128 + pk; \
;         _Pragma("unroll") for (int j = 0; j < 16; ++j) { const size_t a_ = rb_ + (size_t)j * 1024; lfr[j] = LOGF[a_]; qr[j] = Q[a_]; kr[j] = KK[a_]; } } while (0)
; __device__ __forceinline__ void hgrn_prepass(LAS unsigned char* lds, bf16* Q, bf16* KK, const float* LOGF, bf16* PBUF, float* DBUF, int bx, int G) {
;     ...
;             float bl[16], kkv[16]; float bsum = 0.f;
; #pragma unroll
;             for (int j = 0; j < 16; ++j) {
;                 const float q = bf2f((unsigned short)qr[j]); const float kk = bf2f((unsigned short)kr[j]);
;                 bsum += lfr[j]; bl[j] = bsum; kkv[j] = kk;
;                 Qt[(16 * pi + j) * 136 + pk] = f2bf(q * __expf(bsum));
;                 Kt[(16 * pi + j) * 136 + pk] = f2bf(kk * __expf(fminf(-bsum, 80.f)));
;             }
;             DEC[pi * 128 + pk] = __expf(bsum);
; #pragma unroll
;             for (int j = 0; j < 16; ++j) K2[(16 * pi + j) * 136 + pk] = f2bf(kkv[j] * __expf(bsum - bl[j]));
;         }
;         if (u + G < 2048) PP_LOAD(u + G);
	v_lshlrev_b32_e32 v104, 16, v70
	v_mul_f32_e32 v104, v119, v104
	v_cvt_pk_bf16_f32 v104, v104, s0
	ds_write_b16 v64, v104
	v_min_f32_e64 v104, -v118, s2
	v_mul_f32_e32 v104, 0x3fb8aa3b, v104
	v_exp_f32_e32 v104, v104
	s_waitcnt vmcnt(40)
	v_add_f32_e32 v120, v118, v93
	v_mul_f32_e32 v121, 0x3fb8aa3b, v120
	v_lshlrev_b32_e32 v117, 16, v71
	v_exp_f32_e32 v121, v121
	v_mul_f32_e32 v104, v104, v117
	v_cvt_pk_bf16_f32 v104, v104, s0
	ds_write_b16 v64, v104 offset:17408
	s_waitcnt vmcnt(39)
	v_lshlrev_b32_e32 v104, 16, v73
	v_mul_f32_e32 v104, v121, v104
	v_cvt_pk_bf16_f32 v104, v104, s0
	ds_write_b16 v65, v104
	v_min_f32_e64 v104, -v120, s2
	v_mul_f32_e32 v104, 0x3fb8aa3b, v104
	v_exp_f32_e32 v104, v104
	s_waitcnt vmcnt(37)
	v_add_f32_e32 v122, v120, v95
	v_mul_f32_e32 v123, 0x3fb8aa3b, v122
	v_lshlrev_b32_e32 v119, 16, v91
	v_exp_f32_e32 v123, v123
	v_mul_f32_e32 v104, v104, v119
	v_cvt_pk_bf16_f32 v104, v104, s0
	ds_write_b16 v65, v104 offset:17408
	s_waitcnt vmcnt(36)
	v_lshlrev_b32_e32 v104, 16, v92
	v_mul_f32_e32 v104, v123, v104
	v_cvt_pk_bf16_f32 v104, v104, s0
	ds_write_b16 v66, v104
	v_min_f32_e64 v104, -v122, s2
	v_mul_f32_e32 v104, 0x3fb8aa3b, v104
	v_exp_f32_e32 v104, v104
	s_waitcnt vmcnt(34)
	v_add_f32_e32 v124, v122, v97
	v_mul_f32_e32 v125, 0x3fb8aa3b, v124
	v_lshlrev_b32_e32 v121, 16, v94
	v_exp_f32_e32 v125, v125
	v_mul_f32_e32 v104, v104, v121
	v_cvt_pk_bf16_f32 v104, v104, s0
	ds_write_b16 v66, v104 offset:17408
	s_waitcnt vmcnt(33)
	v_lshlrev_b32_e32 v104, 16, v96
	v_mul_f32_e32 v104, v125, v104
	v_cvt_pk_bf16_f32 v104, v104, s0
	ds_write_b16 v67, v104
	v_min_f32_e64 v104, -v124, s2
	v_sub_f32_e32 v3, v124, v3
	v_mul_f32_e32 v104, 0x3fb8aa3b, v104
	v_mul_f32_e32 v3, 0x3fb8aa3b, v3
	v_exp_f32_e32 v104, v104
	v_exp_f32_e32 v3, v3
	s_waitcnt vmcnt(32)
	v_lshlrev_b32_e32 v123, 16, v98
	s_add_i32 s74, s24, s84
	v_mul_f32_e32 v104, v104, v123
	v_mul_f32_e32 v2, v3, v2
	v_cvt_pk_bf16_f32 v104, v104, s0
	v_cvt_pk_bf16_f32 v2, v2, s0
	ds_write_b16 v67, v104 offset:17408
	ds_write_b32 v47, v125 offset:65280
	ds_write_b16 v74, v2 offset:34816
	v_sub_f32_e32 v2, v124, v5
	v_mul_f32_e32 v2, 0x3fb8aa3b, v2
	v_exp_f32_e32 v2, v2
	s_cmpk_gt_i32 s74, 0x7ff
	s_cselect_b64 s[28:29], -1, 0
	s_and_b64 vcc, exec, s[28:29]
	v_mul_f32_e32 v2, v2, v4
	v_cvt_pk_bf16_f32 v2, v2, s0
	ds_write_b16 v53, v2 offset:34816
	v_sub_f32_e32 v2, v124, v12
	v_mul_f32_e32 v2, 0x3fb8aa3b, v2
	v_exp_f32_e32 v2, v2
	s_nop 0
	v_mul_f32_e32 v2, v2, v11
	v_cvt_pk_bf16_f32 v2, v2, s0
	ds_write_b16 v53, v2 offset:35088
	v_sub_f32_e32 v2, v124, v99
	v_mul_f32_e32 v2, 0x3fb8aa3b, v2
	v_exp_f32_e32 v2, v2
	s_nop 0
	v_mul_f32_e32 v2, v2, v13
	v_cvt_pk_bf16_f32 v2, v2, s0
	ds_write_b16 v53, v2 offset:35360
	v_sub_f32_e32 v2, v124, v101
	v_mul_f32_e32 v2, 0x3fb8aa3b, v2
	v_exp_f32_e32 v2, v2
	s_nop 0
	v_mul_f32_e32 v2, v2, v100
	v_cvt_pk_bf16_f32 v2, v2, s0
	ds_write_b16 v53, v2 offset:35632
	v_sub_f32_e32 v2, v124, v103
	v_mul_f32_e32 v2, 0x3fb8aa3b, v2
	v_exp_f32_e32 v2, v2
	s_nop 0
	v_mul_f32_e32 v2, v2, v102
	v_cvt_pk_bf16_f32 v2, v2, s0
	ds_write_b16 v53, v2 offset:35904
	v_sub_f32_e32 v2, v124, v106
	v_mul_f32_e32 v2, 0x3fb8aa3b, v2
	v_exp_f32_e32 v2, v2
	s_nop 0
	v_mul_f32_e32 v2, v2, v105
	v_cvt_pk_bf16_f32 v2, v2, s0
	ds_write_b16 v53, v2 offset:36176
	v_sub_f32_e32 v2, v124, v108
	v_mul_f32_e32 v2, 0x3fb8aa3b, v2
	v_exp_f32_e32 v2, v2
	s_nop 0
	v_mul_f32_e32 v2, v2, v107
	v_cvt_pk_bf16_f32 v2, v2, s0
	ds_write_b16 v53, v2 offset:36448
	v_sub_f32_e32 v2, v124, v110
	v_mul_f32_e32 v2, 0x3fb8aa3b, v2
	v_exp_f32_e32 v2, v2
	s_nop 0
	v_mul_f32_e32 v2, v2, v109
	v_cvt_pk_bf16_f32 v2, v2, s0
	ds_write_b16 v53, v2 offset:36720
	v_sub_f32_e32 v2, v124, v112
	v_mul_f32_e32 v2, 0x3fb8aa3b, v2
	v_exp_f32_e32 v2, v2
	s_nop 0
	v_mul_f32_e32 v2, v2, v111
	v_cvt_pk_bf16_f32 v2, v2, s0
	ds_write_b16 v53, v2 offset:36992
	v_sub_f32_e32 v2, v124, v114
	v_mul_f32_e32 v2, 0x3fb8aa3b, v2
	v_exp_f32_e32 v2, v2
	s_nop 0
	v_mul_f32_e32 v2, v2, v113
	v_cvt_pk_bf16_f32 v2, v2, s0
	ds_write_b16 v53, v2 offset:37264
	v_sub_f32_e32 v2, v124, v116
	v_mul_f32_e32 v2, 0x3fb8aa3b, v2
	v_exp_f32_e32 v2, v2
	s_nop 0
	v_mul_f32_e32 v2, v2, v115
	v_cvt_pk_bf16_f32 v2, v2, s0
	ds_write_b16 v53, v2 offset:37536
	v_sub_f32_e32 v2, v124, v118
	v_mul_f32_e32 v2, 0x3fb8aa3b, v2
	v_exp_f32_e32 v2, v2
	s_nop 0
	v_mul_f32_e32 v2, v2, v117
	v_cvt_pk_bf16_f32 v2, v2, s0
	ds_write_b16 v53, v2 offset:37808
	v_sub_f32_e32 v2, v124, v120
	v_mul_f32_e32 v2, 0x3fb8aa3b, v2
	v_exp_f32_e32 v2, v2
	s_nop 0
	v_mul_f32_e32 v2, v2, v119
	v_cvt_pk_bf16_f32 v2, v2, s0
	ds_write_b16 v53, v2 offset:38080
	v_sub_f32_e32 v2, v124, v122
	v_mul_f32_e32 v2, 0x3fb8aa3b, v2
	v_exp_f32_e32 v2, v2
	s_nop 0
	v_mul_f32_e32 v2, v2, v121
	v_cvt_pk_bf16_f32 v2, v2, s0
	ds_write_b16 v53, v2 offset:38352
	v_sub_f32_e32 v2, v124, v124
	v_mul_f32_e32 v2, 0x3fb8aa3b, v2
	v_exp_f32_e32 v2, v2
	s_nop 0
	v_mul_f32_e32 v2, v2, v123
	v_cvt_pk_bf16_f32 v2, v2, s0
	ds_write_b16 v53, v2 offset:38624
	s_cbranch_vccnz .LBB0_1159
; #define PP_LOAD(uu) do { const int c_ = (uu) & 31, bh_ = (uu) >> 5; const size_t rb_ = ((size_t)(bh_ >> 3) * SEQL + 64 * c_ + 16 * pi) * 1024 + (size_t)(bh_ & 7) * 128 + pk; \
;         _Pragma("unroll") for (int j = 0; j < 16; ++j) { const size_t a_ = rb_ + (size_t)j * 1024; lfr[j] = LOGF[a_]; qr[j] = Q[a_]; kr[j] = KK[a_]; } } while (0)
; __device__ __forceinline__ void hgrn_prepass(LAS unsigned char* lds, bf16* Q, bf16* KK, const float* LOGF, bf16* PBUF, float* DBUF, int bx, int G) {
;     ...
;         if (u + G < 2048) PP_LOAD(u + G);
	s_lshl_b32 s20, s74, 6
	s_ashr_i32 s2, s74, 8
	s_and_b32 s26, s20, 0x7c0
	s_ashr_i32 s3, s2, 31
	v_lshl_add_u64 v[2:3], s[26:27], 0, v[6:7]
	s_lshl_b64 s[2:3], s[2:3], 21
	v_lshlrev_b64 v[2:3], 10, v[2:3]
	v_lshl_add_u64 v[2:3], v[2:3], 0, s[2:3]
	s_lshl_b32 s2, s74, 2
	s_and_b32 s2, s2, 0x380
	v_readlane_b32 s20, v253, 15
	v_or3_b32 v2, s2, v1, v2
	v_readlane_b32 s21, v253, 16
	v_readlane_b32 s2, v253, 0
	v_readlane_b32 s3, v253, 1
	v_lshl_add_u64 v[4:5], v[2:3], 2, s[20:21]
	global_load_dword v16, v[4:5], off nt
	v_lshlrev_b64 v[4:5], 1, v[2:3]
	v_lshl_add_u64 v[12:13], s[34:35], 0, v[4:5]
	v_lshl_add_u64 v[4:5], s[2:3], 0, v[4:5]
	global_load_ushort v15, v[12:13], off nt
	global_load_ushort v17, v[4:5], off nt
	v_or_b32_e32 v4, 0x400, v2
	v_mov_b32_e32 v5, v3
	v_lshl_add_u64 v[12:13], v[4:5], 2, s[20:21]
	v_lshlrev_b64 v[4:5], 1, v[4:5]
	global_load_dword v19, v[12:13], off nt
	v_lshl_add_u64 v[12:13], s[34:35], 0, v[4:5]
	v_lshl_add_u64 v[4:5], s[2:3], 0, v[4:5]
	global_load_ushort v18, v[12:13], off nt
	global_load_ushort v20, v[4:5], off nt
	v_or_b32_e32 v4, 0x800, v2
	v_mov_b32_e32 v5, v3
	v_lshl_add_u64 v[12:13], v[4:5], 2, s[20:21]
	v_lshlrev_b64 v[4:5], 1, v[4:5]
	global_load_dword v21, v[12:13], off nt
	v_lshl_add_u64 v[12:13], s[34:35], 0, v[4:5]
	v_lshl_add_u64 v[4:5], s[2:3], 0, v[4:5]
	global_load_ushort v22, v[12:13], off nt
	global_load_ushort v23, v[4:5], off nt
	v_or_b32_e32 v4, 0xc00, v2
	v_mov_b32_e32 v5, v3
	v_lshl_add_u64 v[12:13], v[4:5], 2, s[20:21]
	v_lshlrev_b64 v[4:5], 1, v[4:5]
	global_load_dword v25, v[12:13], off nt
	v_lshl_add_u64 v[12:13], s[34:35], 0, v[4:5]
	v_lshl_add_u64 v[4:5], s[2:3], 0, v[4:5]
	global_load_ushort v24, v[12:13], off nt
	global_load_ushort v26, v[4:5], off nt
	v_or_b32_e32 v4, 0x1000, v2
	v_mov_b32_e32 v5, v3
	v_lshl_add_u64 v[12:13], v[4:5], 2, s[20:21]
	v_lshlrev_b64 v[4:5], 1, v[4:5]
	global_load_dword v28, v[12:13], off nt
	v_lshl_add_u64 v[12:13], s[34:35], 0, v[4:5]
	v_lshl_add_u64 v[4:5], s[2:3], 0, v[4:5]
	global_load_ushort v27, v[12:13], off nt
	global_load_ushort v29, v[4:5], off nt
	v_or_b32_e32 v4, 0x1400, v2
	v_mov_b32_e32 v5, v3
	v_lshl_add_u64 v[12:13], v[4:5], 2, s[20:21]
	v_lshlrev_b64 v[4:5], 1, v[4:5]
	global_load_dword v31, v[12:13], off nt
	v_lshl_add_u64 v[12:13], s[34:35], 0, v[4:5]
	v_lshl_add_u64 v[4:5], s[2:3], 0, v[4:5]
	global_load_ushort v30, v[12:13], off nt
	global_load_ushort v32, v[4:5], off nt
	v_or_b32_e32 v4, 0x1800, v2
	v_mov_b32_e32 v5, v3
	v_lshl_add_u64 v[12:13], v[4:5], 2, s[20:21]
	v_lshlrev_b64 v[4:5], 1, v[4:5]
	global_load_dword v34, v[12:13], off nt
	v_lshl_add_u64 v[12:13], s[34:35], 0, v[4:5]
	v_lshl_add_u64 v[4:5], s[2:3], 0, v[4:5]
	global_load_ushort v33, v[12:13], off nt
	global_load_ushort v35, v[4:5], off nt
	v_or_b32_e32 v4, 0x1c00, v2
	v_mov_b32_e32 v5, v3
	v_lshl_add_u64 v[12:13], v[4:5], 2, s[20:21]
	v_lshlrev_b64 v[4:5], 1, v[4:5]
	global_load_dword v37, v[12:13], off nt
	v_lshl_add_u64 v[12:13], s[34:35], 0, v[4:5]
	v_lshl_add_u64 v[4:5], s[2:3], 0, v[4:5]
	global_load_ushort v36, v[12:13], off nt
	global_load_ushort v38, v[4:5], off nt
	v_or_b32_e32 v4, 0x2000, v2
	v_mov_b32_e32 v5, v3
	v_lshl_add_u64 v[12:13], v[4:5], 2, s[20:21]
	v_lshlrev_b64 v[4:5], 1, v[4:5]
	global_load_dword v40, v[12:13], off nt
	v_lshl_add_u64 v[12:13], s[34:35], 0, v[4:5]
	v_lshl_add_u64 v[4:5], s[2:3], 0, v[4:5]
	global_load_ushort v39, v[12:13], off nt
	global_load_ushort v41, v[4:5], off nt
	v_or_b32_e32 v4, 0x2400, v2
	v_mov_b32_e32 v5, v3
	v_lshl_add_u64 v[12:13], v[4:5], 2, s[20:21]
	v_lshlrev_b64 v[4:5], 1, v[4:5]
	global_load_dword v43, v[12:13], off nt
	v_lshl_add_u64 v[12:13], s[34:35], 0, v[4:5]
	v_lshl_add_u64 v[4:5], s[2:3], 0, v[4:5]
	global_load_ushort v42, v[12:13], off nt
	global_load_ushort v44, v[4:5], off nt
	v_or_b32_e32 v4, 0x2800, v2
	v_mov_b32_e32 v5, v3
	v_lshl_add_u64 v[12:13], v[4:5], 2, s[20:21]
	v_lshlrev_b64 v[4:5], 1, v[4:5]
	global_load_dword v45, v[12:13], off nt
	v_lshl_add_u64 v[12:13], s[34:35], 0, v[4:5]
	v_lshl_add_u64 v[4:5], s[2:3], 0, v[4:5]
	global_load_ushort v46, v[12:13], off nt
	global_load_ushort v49, v[4:5], off nt
	v_or_b32_e32 v4, 0x2c00, v2
	v_mov_b32_e32 v5, v3
	v_lshl_add_u64 v[12:13], v[4:5], 2, s[20:21]
	v_lshlrev_b64 v[4:5], 1, v[4:5]
	global_load_dword v69, v[12:13], off nt
	v_lshl_add_u64 v[12:13], s[34:35], 0, v[4:5]
	v_lshl_add_u64 v[4:5], s[2:3], 0, v[4:5]
	global_load_ushort v52, v[12:13], off nt
	global_load_ushort v68, v[4:5], off nt
	v_or_b32_e32 v4, 0x3000, v2
	v_mov_b32_e32 v5, v3
	v_lshl_add_u64 v[12:13], v[4:5], 2, s[20:21]
	v_lshlrev_b64 v[4:5], 1, v[4:5]
	global_load_dword v72, v[12:13], off nt
	v_lshl_add_u64 v[12:13], s[34:35], 0, v[4:5]
	v_lshl_add_u64 v[4:5], s[2:3], 0, v[4:5]
	global_load_ushort v70, v[12:13], off nt
	global_load_ushort v71, v[4:5], off nt
	v_or_b32_e32 v4, 0x3400, v2
	v_mov_b32_e32 v5, v3
	v_lshl_add_u64 v[12:13], v[4:5], 2, s[20:21]
	v_lshlrev_b64 v[4:5], 1, v[4:5]
	global_load_dword v93, v[12:13], off nt
	v_lshl_add_u64 v[12:13], s[34:35], 0, v[4:5]
	v_lshl_add_u64 v[4:5], s[2:3], 0, v[4:5]
	global_load_ushort v73, v[12:13], off nt
	global_load_ushort v91, v[4:5], off nt
	v_or_b32_e32 v4, 0x3800, v2
	v_mov_b32_e32 v5, v3
	v_lshl_add_u64 v[12:13], v[4:5], 2, s[20:21]
	v_lshlrev_b64 v[4:5], 1, v[4:5]
	global_load_dword v95, v[12:13], off nt
	v_lshl_add_u64 v[12:13], s[34:35], 0, v[4:5]
	v_lshl_add_u64 v[4:5], s[2:3], 0, v[4:5]
	v_or_b32_e32 v2, 0x3c00, v2
	global_load_ushort v92, v[12:13], off nt
	global_load_ushort v94, v[4:5], off nt
	v_lshl_add_u64 v[4:5], v[2:3], 2, s[20:21]
	v_lshlrev_b64 v[2:3], 1, v[2:3]
	global_load_dword v97, v[4:5], off nt
	v_lshl_add_u64 v[4:5], s[34:35], 0, v[2:3]
	v_lshl_add_u64 v[2:3], s[2:3], 0, v[2:3]
	global_load_ushort v96, v[4:5], off nt
	global_load_ushort v98, v[2:3], off nt
